# attention prompt: PV V^T reads batched + next-head Q/sink prefetch; on top of v14
# speedup vs baseline: 1.0102x; 1.0009x over previous
; DEV f32x4 mfma32(bf16x8 a, bf16x8 b, f32x4 c) { return __builtin_amdgcn_mfma_f32_16x16x32_bf16(a, b, c, 0, 0, 0); }
; DEV void attn_prompt_group(const Params& p, int l, int item, unsigned char* smem) {
;     ...
;   __syncthreads();
;   const int qi0 = w * 16 + fr;
; #pragma unroll 1
;   for (int g = 0; g < 4; ++g) {
;     const int h = kvh * 4 + g;
;     int qi = qi0; asm volatile("" : "+v"(qi));
;     bf16x8 qf[2];
; #pragma unroll
;     for (int ks = 0; ks < 2; ++ks) qf[ks] = __builtin_bit_cast(bf16x8, *(const u32x4*)(Z + (rowbase + qi) * NIN + AQ + h * 64 + ks * 32 + fq * 8));
;     f32x4 s[9];
; #pragma unroll
;     for (int t = 0; t < 9; ++t) {
;       s[t] = (f32x4){0.f, 0.f, 0.f, 0.f};
; #pragma unroll
;       for (int ks = 0; ks < 2; ++ks) s[t] = mfma32(kf[t][ks], qf[ks], s[t]);
;     }
;     const float slope = exp2f(-(float)(h + 1));
;     const float sink = p.in[I_SINKS][l * 8 + h];
;     float mx = sink;
; #pragma unroll
;     for (int t = 0; t < 9; ++t)
; #pragma unroll
;       for (int j = 0; j < 4; ++j) {
;         const int si = (w + t) * 16 + fq * 4 + j;
;         const bool ok = (si > qi) && (si <= 128 + qi) && (nb > 0 || si >= 128);
.LBB0_476:
	s_or_b64 exec, exec, s[2:3]
	v_cndmask_b32_e64 v72, 0, 1, s[34:35]
	v_readlane_b32 s2, v248, 46
	v_readfirstlane_b32 s1, v72
	s_lshl_b32 s1, s1, 2
	s_add_i32 s2, s2, s1
	s_ashr_i32 s3, s2, 31
	s_lshl_b64 s[2:3], s[2:3], 2
	s_add_u32 s18, s82, s2
	s_addc_u32 s19, s83, s3
	s_or_b32 s6, s1, 1
	v_lshlrev_b32_e32 v107, 2, v78
	s_cmp_lg_u32 s8, 0
	v_or_b32_e32 v108, v107, v75
	s_movk_i32 s1, 0x7f
	s_cselect_b64 s[88:89], -1, 0
	v_cmp_lt_i32_e32 vcc, s1, v108
	s_movk_i32 s84, 0x7e
	s_or_b64 s[36:37], s[88:89], vcc
	v_cmp_lt_i32_e32 vcc, s84, v108
	v_or_b32_e32 v110, 2, v108
	s_or_b64 s[38:39], s[88:89], vcc
	v_cmp_lt_i32_e32 vcc, s1, v110
	v_or_b32_e32 v111, 3, v108
	s_or_b64 s[40:41], s[88:89], vcc
	v_cmp_lt_i32_e32 vcc, s1, v111
	v_or_b32_e32 v112, v81, v107
	s_or_b64 s[60:61], s[88:89], vcc
	v_cmp_lt_i32_e32 vcc, s1, v112
	s_or_b64 s[62:63], s[88:89], vcc
	v_cmp_lt_i32_e32 vcc, s84, v112
	v_or_b32_e32 v114, 2, v112
	s_or_b64 s[64:65], s[88:89], vcc
	v_cmp_lt_i32_e32 vcc, s1, v114
	v_or_b32_e32 v115, 3, v112
	s_or_b64 s[66:67], s[88:89], vcc
	v_cmp_lt_i32_e32 vcc, s1, v115
	v_or_b32_e32 v116, v83, v107
	s_or_b64 s[68:69], s[88:89], vcc
	v_cmp_lt_i32_e32 vcc, s1, v116
	s_or_b64 s[70:71], s[88:89], vcc
	v_cmp_lt_i32_e32 vcc, s84, v116
	v_or_b32_e32 v118, 2, v116
	s_or_b64 s[72:73], s[88:89], vcc
	v_cmp_lt_i32_e32 vcc, s1, v118
	v_or_b32_e32 v119, 3, v116
	v_add_u32_e32 v98, 0, v84
	v_mul_lo_u32 v84, v77, s75
	s_or_b64 s[74:75], s[88:89], vcc
	v_cmp_lt_i32_e32 vcc, s1, v119
	v_or_b32_e32 v120, v86, v107
	s_or_b64 s[96:97], s[88:89], vcc
	v_cmp_lt_i32_e32 vcc, s1, v120
	s_or_b64 s[4:5], s[88:89], vcc
	v_cmp_lt_i32_e32 vcc, s84, v120
	v_or_b32_e32 v122, 2, v120
	s_or_b64 s[26:27], s[88:89], vcc
	v_cmp_lt_i32_e32 vcc, s1, v122
	v_or_b32_e32 v123, 3, v120
	s_or_b64 s[20:21], s[88:89], vcc
	v_cmp_lt_i32_e32 vcc, s1, v123
	v_or_b32_e32 v124, v88, v107
	s_or_b64 s[44:45], s[88:89], vcc
	v_cmp_lt_i32_e32 vcc, s1, v124
	s_or_b64 s[46:47], s[88:89], vcc
	v_cmp_lt_i32_e32 vcc, s84, v124
	v_or_b32_e32 v126, 2, v124
	s_or_b64 s[48:49], s[88:89], vcc
	v_cmp_lt_i32_e32 vcc, s1, v126
	v_or_b32_e32 v127, 3, v124
	s_or_b64 s[50:51], s[88:89], vcc
	v_cmp_lt_i32_e32 vcc, s1, v127
	v_or_b32_e32 v128, v89, v107
	s_or_b64 s[52:53], s[88:89], vcc
	v_cmp_lt_i32_e32 vcc, s1, v128
	s_or_b64 s[54:55], s[88:89], vcc
	v_cmp_lt_i32_e32 vcc, s84, v128
	v_or_b32_e32 v130, 2, v128
	s_or_b64 s[56:57], s[88:89], vcc
	v_cmp_lt_i32_e32 vcc, s1, v130
	v_or_b32_e32 v131, 3, v128
	s_or_b64 s[58:59], s[88:89], vcc
	v_cmp_lt_i32_e32 vcc, s1, v131
	v_or_b32_e32 v132, v93, v107
	s_or_b64 s[42:43], s[88:89], vcc
	v_cmp_lt_i32_e32 vcc, s1, v132
	s_or_b64 s[2:3], s[88:89], vcc
	v_cmp_lt_i32_e32 vcc, s84, v132
	v_or_b32_e32 v134, 2, v132
	s_mul_i32 s92, s8, 0x1b0000
	s_or_b64 s[8:9], s[88:89], vcc
	v_cmp_lt_i32_e32 vcc, s1, v134
	v_or_b32_e32 v135, 3, v132
	s_or_b64 s[12:13], s[88:89], vcc
	v_cmp_lt_i32_e32 vcc, s1, v135
	v_or_b32_e32 v136, v95, v107
	s_or_b64 s[14:15], s[88:89], vcc
	v_cmp_lt_i32_e32 vcc, s1, v136
	s_or_b64 s[16:17], s[88:89], vcc
	v_cmp_lt_i32_e32 vcc, s84, v136
	v_or_b32_e32 v138, 2, v136
	s_or_b64 s[76:77], s[88:89], vcc
	v_cmp_lt_i32_e32 vcc, s1, v138
	v_or_b32_e32 v139, 3, v136
	s_or_b64 s[78:79], s[88:89], vcc
	v_cmp_lt_i32_e32 vcc, s1, v139
	v_or_b32_e32 v140, v97, v107
	s_or_b64 s[80:81], s[88:89], vcc
	v_cmp_lt_i32_e32 vcc, s1, v140
	s_or_b64 s[82:83], s[88:89], vcc
	v_cmp_lt_i32_e32 vcc, s84, v140
	v_or_b32_e32 v142, 2, v140
	s_or_b64 s[84:85], s[88:89], vcc
	v_cmp_lt_i32_e32 vcc, s1, v142
	v_or_b32_e32 v143, 3, v140
	v_lshlrev_b32_e32 v99, 4, v74
	s_or_b64 s[86:87], s[88:89], vcc
	v_cmp_lt_i32_e32 vcc, s1, v143
	v_and_b32_e32 v92, 63, v74
	v_add_u32_e32 v91, 0, v84
	v_and_b32_e32 v99, 0x70, v99
	s_or_b64 s[88:89], s[88:89], vcc
	s_mul_i32 s91, s0, 0x3600000
	v_lshl_add_u32 v84, v76, 1, v91
	v_add_u32_e32 v91, v91, v99
	v_lshrrev_b32_e32 v99, 3, v92
	s_mul_hi_i32 s90, s0, 0x3600000
	s_add_u32 s0, s91, s92
	v_or_b32_e32 v106, v75, v76
	v_bitop3_b32 v113, v81, v107, v81 bitop3:3
	v_mul_u32_u24_e32 v81, 0x210, v76
	v_or_b32_e32 v76, 8, v99
	s_addc_u32 s1, s90, 0
	v_bitop3_b32 v117, v83, v107, v83 bitop3:3
	v_bitop3_b32 v133, v93, v107, v93 bitop3:3
	v_lshl_add_u32 v83, v77, 5, v98
	v_mul_u32_u24_e32 v93, 0x90, v76
	v_mov_b64_e32 v[76:77], s[0:1]
	v_mad_u64_u32 v[76:77], s[0:1], v99, s95, v[76:77]
	v_lshlrev_b32_e32 v72, 9, v72
	v_mov_b32_e32 v73, v169
	v_mad_i64_i32 v[76:77], s[0:1], v75, s95, v[76:77]
	v_lshl_add_u64 v[76:77], v[76:77], 0, v[72:73]
	v_and_b32_e32 v73, 7, v74
	v_or_b32_e32 v144, 1, v107
	v_lshl_or_b32 v76, v73, 4, v76
	v_or_b32_e32 v72, s91, v72
	v_mov_b32_e32 v73, s90
	v_mul_u32_u24_e32 v92, 0x90, v99
	v_bitop3_b32 v121, v86, v107, v86 bitop3:3
	v_bitop3_b32 v125, v88, v107, v88 bitop3:3
	v_bitop3_b32 v129, v89, v107, v89 bitop3:3
	v_lshl_add_u32 v79, v79, 5, v98
	v_lshl_add_u32 v80, v80, 5, v98
	v_lshl_add_u32 v82, v82, 5, v98
	v_lshl_add_u32 v85, v85, 5, v98
	v_lshl_add_u32 v86, v87, 5, v98
	v_lshl_add_u32 v87, v90, 5, v98
	v_lshl_add_u32 v88, v94, 5, v98
	v_lshl_add_u32 v89, v96, 5, v98
	v_mul_u32_u24_e32 v78, 0x240, v78
	v_mul_u32_u24_e32 v90, 0x90, v144
	v_lshl_add_u64 v[72:73], s[28:29], 0, v[72:73]
	v_bitop3_b32 v109, v107, v75, v107 bitop3:3
	v_bitop3_b32 v137, v95, v107, v95 bitop3:3
	v_bitop3_b32 v141, v97, v107, v97 bitop3:3
	v_or_b32_e32 v145, 2, v107
	v_or_b32_e32 v146, 3, v107
	v_lshl_add_u64 v[100:101], s[28:29], 0, v[76:77]
	v_lshl_add_u64 v[102:103], v[72:73], 0, v[168:169]
	s_mov_b64 s[90:91], 0
	v_add_u32_e32 v147, v83, v81
	v_add_u32_e32 v148, v79, v81
	v_add_u32_e32 v149, v80, v81
	v_add_u32_e32 v150, v82, v81
	v_add_u32_e32 v151, v85, v81
	v_add_u32_e32 v152, v86, v81
	v_add_u32_e32 v153, v87, v81
	v_add_u32_e32 v154, v88, v81
	v_add_u32_e32 v155, v89, v81
	v_add_u32_e32 v156, v84, v78
	v_add_u32_e32 v157, v84, v90
	v_add_u32_e32 v158, v91, v92
	v_add_u32_e32 v159, v91, v93
	s_mov_b32 s94, 0x42fc0000
	s_mov_b32 s0, s92
	s_mov_b32 s1, 0
	v_mov_b64_e32 v[72:73], s[0:1]
	v_mad_i64_i32 v[72:73], s[0:1], v106, s95, v[72:73]
	v_lshl_add_u64 v[72:73], v[102:103], 0, v[72:73]
	v_add_co_u32_e32 v76, vcc, 0x4700000, v72
	s_nop 1
	v_addc_co_u32_e32 v77, vcc, 0, v73, vcc
	global_load_dwordx4 v[234:237], v[76:77], off offset:3072
	global_load_dwordx4 v[238:241], v[76:77], off offset:3136
	global_load_dword v242, v169, s[18:19]
	s_waitcnt lgkmcnt(0)
	s_barrier
	s_waitcnt vmcnt(0)
; DEV f32x4 mfma32(bf16x8 a, bf16x8 b, f32x4 c) { return __builtin_amdgcn_mfma_f32_16x16x32_bf16(a, b, c, 0, 0, 0); }
; DEV void attn_prompt_group(const Params& p, int l, int item, unsigned char* smem) {
;     ...
;   for (int g = 0; g < 4; ++g) {
;     const int h = kvh * 4 + g;
;     int qi = qi0; asm volatile("" : "+v"(qi));
;     bf16x8 qf[2];
; #pragma unroll
;     for (int ks = 0; ks < 2; ++ks) qf[ks] = __builtin_bit_cast(bf16x8, *(const u32x4*)(Z + (rowbase + qi) * NIN + AQ + h * 64 + ks * 32 + fq * 8));
;     f32x4 s[9];
; #pragma unroll
;     for (int t = 0; t < 9; ++t) {
;       s[t] = (f32x4){0.f, 0.f, 0.f, 0.f};
; #pragma unroll
;       for (int ks = 0; ks < 2; ++ks) s[t] = mfma32(kf[t][ks], qf[ks], s[t]);
;     }
;     const float slope = exp2f(-(float)(h + 1));
;     const float sink = p.in[I_SINKS][l * 8 + h];
;     float mx = sink;
; #pragma unroll
;     for (int t = 0; t < 9; ++t)
; #pragma unroll
;       for (int j = 0; j < 4; ++j) {
;         const int si = (w + t) * 16 + fq * 4 + j;
;         const bool ok = (si > qi) && (si <= 128 + qi) && (nb > 0 || si >= 128);
;         const float sc = ok ? s[t][j] * 0.125f - slope * (float)(128 + qi - si) : -INFINITY;
;         s[t][j] = sc; mx = fmaxf(mx, sc);
;       }
.LBB0_477:
	s_add_u32 s0, s90, s92
	s_addc_u32 s1, s91, 0
	v_mov_b32_e32 v177, v106
	v_mov_b64_e32 v[72:73], s[0:1]
	v_cvt_f32_u32_e32 v104, s6
	v_mad_i64_i32 v[72:73], s[0:1], v177, s95, v[72:73]
	v_lshl_add_u64 v[72:73], v[102:103], 0, v[72:73]
	v_add_co_u32_e32 v76, vcc, 0x4700000, v72
	v_add_u32_e32 v184, 0x80, v177
	s_nop 0
	v_addc_co_u32_e32 v77, vcc, 0, v73, vcc
	v_mov_b64_e32 v[72:73], v[234:235]
	v_mov_b64_e32 v[74:75], v[236:237]
	v_mov_b64_e32 v[160:161], v[238:239]
	v_mov_b64_e32 v[162:163], v[240:241]
	s_cmp_eq_u32 s90, 0x180
	s_cbranch_scc1 .Lattn_noq
	global_load_dwordx4 v[234:237], v[76:77], off offset:3200
	global_load_dwordx4 v[238:241], v[76:77], off offset:3264
.Lattn_noq:
	v_cmp_lt_f32_e32 vcc, s94, v104
	s_and_b64 s[0:1], vcc, exec
	s_cselect_b32 s0, 0xffffffc0, 0
	v_cndmask_b32_e32 v105, 0, v203, vcc
	v_sub_f32_e32 v104, v105, v104
	v_exp_f32_e32 v104, v104
	v_cmp_gt_i32_e32 vcc, v108, v177
	v_mfma_f32_16x16x32_bf16 v[76:79], v[4:7], v[72:75], 0
	v_ldexp_f32 v105, v104, s0
	v_sub_u32_e32 v104, v184, v108
	v_cvt_f32_i32_e32 v179, v104
	v_mfma_f32_16x16x32_bf16 v[164:167], v[0:3], v[160:163], v[76:79]
	v_cmp_ge_i32_e64 s[0:1], v184, v108
	s_and_b64 s[0:1], vcc, s[0:1]
	s_and_b64 vcc, s[36:37], s[0:1]
	v_mfma_f32_16x16x32_bf16 v[76:79], v[12:15], v[72:75], 0
	v_cmp_gt_i32_e64 s[0:1], v184, v108
	s_nop 2
	v_mov_b32_e32 v104, v164
	v_mfma_f32_16x16x32_bf16 v[180:183], v[8:11], v[160:163], v[76:79]
	v_mfma_f32_16x16x32_bf16 v[76:79], v[20:23], v[72:75], 0
	v_mfma_f32_16x16x32_bf16 v[96:99], v[16:19], v[160:163], v[76:79]
	v_mfma_f32_16x16x32_bf16 v[76:79], v[28:31], v[72:75], 0
	v_mfma_f32_16x16x32_bf16 v[92:95], v[24:27], v[160:163], v[76:79]
	v_mfma_f32_16x16x32_bf16 v[76:79], v[36:39], v[72:75], 0
	v_mfma_f32_16x16x32_bf16 v[88:91], v[32:35], v[160:163], v[76:79]
	v_mfma_f32_16x16x32_bf16 v[76:79], v[44:47], v[72:75], 0
	v_mfma_f32_16x16x32_bf16 v[84:87], v[40:43], v[160:163], v[76:79]
	v_mfma_f32_16x16x32_bf16 v[76:79], v[52:55], v[72:75], 0
	v_mfma_f32_16x16x32_bf16 v[80:83], v[48:51], v[160:163], v[76:79]
	v_mfma_f32_16x16x32_bf16 v[76:79], v[60:63], v[72:75], 0
	v_mfma_f32_16x16x32_bf16 v[72:75], v[68:71], v[72:75], 0
	v_mfma_f32_16x16x32_bf16 v[76:79], v[56:59], v[160:163], v[76:79]
	v_mfma_f32_16x16x32_bf16 v[72:75], v[64:67], v[160:163], v[72:75]
	v_mov_b32_e32 v160, v242
	s_cmp_eq_u32 s90, 0x180
	s_cbranch_scc1 .Lattn_nos
	global_load_dword v242, v169, s[18:19] offset:4
.Lattn_nos:
	v_pk_mul_f32 v[162:163], v[104:105], v[178:179]
	s_nop 0
	v_sub_f32_e32 v104, v162, v163
	v_cndmask_b32_e32 v161, v205, v104, vcc
	v_add_u32_e32 v104, v184, v109
	v_cvt_f32_i32_e32 v179, v104
	v_cmp_ge_i32_e32 vcc, v108, v177
	v_mov_b32_e32 v104, v165
	s_and_b64 s[0:1], vcc, s[0:1]
	v_pk_mul_f32 v[162:163], v[104:105], v[178:179]
	s_and_b64 vcc, s[38:39], s[0:1]
	v_sub_f32_e32 v104, v162, v163
	v_cndmask_b32_e32 v162, v205, v104, vcc
	v_sub_u32_e32 v104, v184, v110
	v_cvt_f32_i32_e32 v179, v104
	v_cmp_gt_i32_e32 vcc, v110, v177
	v_cmp_ge_i32_e64 s[0:1], v184, v110
	v_mov_b32_e32 v104, v166
	s_and_b64 s[0:1], vcc, s[0:1]
	v_pk_mul_f32 v[164:165], v[104:105], v[178:179]
	s_and_b64 vcc, s[40:41], s[0:1]
	v_sub_f32_e32 v104, v164, v165
	v_cndmask_b32_e32 v163, v205, v104, vcc
	v_sub_u32_e32 v104, v184, v111
	v_cvt_f32_i32_e32 v179, v104
	v_cmp_gt_i32_e32 vcc, v111, v177
	v_cmp_ge_i32_e64 s[0:1], v184, v111
	v_mov_b32_e32 v104, v167
	s_and_b64 s[0:1], vcc, s[0:1]
	v_pk_mul_f32 v[164:165], v[104:105], v[178:179]
	s_and_b64 vcc, s[60:61], s[0:1]
	v_sub_f32_e32 v104, v164, v165
	v_cndmask_b32_e32 v164, v205, v104, vcc
	v_sub_u32_e32 v104, v184, v112
	v_cvt_f32_i32_e32 v179, v104
	v_cmp_gt_i32_e32 vcc, v112, v177
	v_cmp_ge_i32_e64 s[0:1], v184, v112
	v_mov_b32_e32 v104, v180
	s_and_b64 s[0:1], vcc, s[0:1]
	v_pk_mul_f32 v[166:167], v[104:105], v[178:179]
	s_and_b64 vcc, s[62:63], s[0:1]
	v_sub_f32_e32 v104, v166, v167
	v_cndmask_b32_e32 v165, v205, v104, vcc
	v_add_u32_e32 v104, v184, v113
	v_cvt_f32_i32_e32 v179, v104
	v_cmp_ge_i32_e32 vcc, v112, v177
	v_cmp_gt_i32_e64 s[0:1], v184, v112
	v_mov_b32_e32 v104, v181
	s_and_b64 s[0:1], vcc, s[0:1]
	v_pk_mul_f32 v[166:167], v[104:105], v[178:179]
	s_and_b64 vcc, s[64:65], s[0:1]
	v_sub_f32_e32 v104, v166, v167
	v_cndmask_b32_e32 v166, v205, v104, vcc
	v_sub_u32_e32 v104, v184, v114
	v_cvt_f32_i32_e32 v179, v104
	v_cmp_gt_i32_e32 vcc, v114, v177
	v_cmp_ge_i32_e64 s[0:1], v184, v114
	v_mov_b32_e32 v104, v182
	s_and_b64 s[0:1], vcc, s[0:1]
	v_pk_mul_f32 v[180:181], v[104:105], v[178:179]
	s_and_b64 vcc, s[66:67], s[0:1]
	v_sub_f32_e32 v104, v180, v181
	v_cndmask_b32_e32 v167, v205, v104, vcc
	v_sub_u32_e32 v104, v184, v115
	v_cvt_f32_i32_e32 v179, v104
	v_cmp_gt_i32_e32 vcc, v115, v177
	v_cmp_ge_i32_e64 s[0:1], v184, v115
	v_mov_b32_e32 v104, v183
	s_and_b64 s[0:1], vcc, s[0:1]
	v_pk_mul_f32 v[180:181], v[104:105], v[178:179]
	s_and_b64 vcc, s[68:69], s[0:1]
	v_sub_f32_e32 v104, v180, v181
	v_cmp_ge_i32_e64 s[0:1], v184, v116
	v_max3_f32 v168, v160, v161, v162
	v_max3_f32 v168, v168, v163, v164
	v_max3_f32 v185, v168, v165, v166
	v_cndmask_b32_e32 v168, v205, v104, vcc
	v_sub_u32_e32 v104, v184, v116
	v_cvt_f32_i32_e32 v179, v104
	v_mov_b32_e32 v104, v96
	v_cmp_gt_i32_e32 vcc, v116, v177
	s_and_b64 s[0:1], vcc, s[0:1]
	v_pk_mul_f32 v[180:181], v[104:105], v[178:179]
	v_add_u32_e32 v104, v184, v117
	v_cvt_f32_i32_e32 v179, v104
	v_mov_b32_e32 v104, v97
	v_sub_f32_e32 v96, v180, v181
	s_and_b64 vcc, s[70:71], s[0:1]
	v_pk_mul_f32 v[180:181], v[104:105], v[178:179]
	v_sub_u32_e32 v104, v184, v118
	v_cvt_f32_i32_e32 v179, v104
	v_mov_b32_e32 v104, v98
	v_sub_f32_e32 v97, v180, v181
; DEV void attn_prompt_group(const Params& p, int l, int item, unsigned char* smem) {
;     ...
; #pragma unroll
;     for (int t = 0; t < 9; ++t)
; #pragma unroll
;       for (int j = 0; j < 4; ++j) {
;         const int si = (w + t) * 16 + fq * 4 + j;
;         const bool ok = (si > qi) && (si <= 128 + qi) && (nb > 0 || si >= 128);
;         const float sc = ok ? s[t][j] * 0.125f - slope * (float)(128 + qi - si) : -INFINITY;
;         s[t][j] = sc; mx = fmaxf(mx, sc);
;       }
	v_cndmask_b32_e32 v96, v205, v96, vcc
	v_pk_mul_f32 v[180:181], v[104:105], v[178:179]
	v_sub_u32_e32 v104, v184, v119
	v_cvt_f32_i32_e32 v179, v104
	v_mov_b32_e32 v104, v99
	v_sub_f32_e32 v98, v180, v181
	v_cmp_ge_i32_e32 vcc, v116, v177
	v_pk_mul_f32 v[180:181], v[104:105], v[178:179]
	v_sub_u32_e32 v104, v184, v120
	v_cvt_f32_i32_e32 v179, v104
	v_mov_b32_e32 v104, v92
	v_sub_f32_e32 v99, v180, v181
	v_cmp_gt_i32_e64 s[0:1], v184, v116
	v_pk_mul_f32 v[180:181], v[104:105], v[178:179]
	v_add_u32_e32 v104, v184, v121
	v_cvt_f32_i32_e32 v179, v104
	v_mov_b32_e32 v104, v93
	v_sub_f32_e32 v92, v180, v181
	s_and_b64 s[0:1], vcc, s[0:1]
	v_pk_mul_f32 v[180:181], v[104:105], v[178:179]
	v_sub_u32_e32 v104, v184, v122
	v_cvt_f32_i32_e32 v179, v104
	v_mov_b32_e32 v104, v94
	v_sub_f32_e32 v93, v180, v181
	s_and_b64 vcc, s[72:73], s[0:1]
	v_pk_mul_f32 v[180:181], v[104:105], v[178:179]
	v_sub_u32_e32 v104, v184, v123
	v_cvt_f32_i32_e32 v179, v104
	v_mov_b32_e32 v104, v95
	v_sub_f32_e32 v94, v180, v181
	v_cndmask_b32_e32 v97, v205, v97, vcc
	v_pk_mul_f32 v[180:181], v[104:105], v[178:179]
	v_sub_u32_e32 v104, v184, v124
	v_cvt_f32_i32_e32 v179, v104
	v_mov_b32_e32 v104, v88
	v_sub_f32_e32 v95, v180, v181
	v_cmp_gt_i32_e32 vcc, v118, v177
	v_pk_mul_f32 v[180:181], v[104:105], v[178:179]
	v_add_u32_e32 v104, v184, v125
	v_cvt_f32_i32_e32 v179, v104
	v_mov_b32_e32 v104, v89
	v_sub_f32_e32 v88, v180, v181
	v_cmp_ge_i32_e64 s[0:1], v184, v118
	v_pk_mul_f32 v[180:181], v[104:105], v[178:179]
	v_sub_u32_e32 v104, v184, v126
	v_cvt_f32_i32_e32 v179, v104
	v_mov_b32_e32 v104, v90
	v_sub_f32_e32 v89, v180, v181
	s_and_b64 s[0:1], vcc, s[0:1]
	v_pk_mul_f32 v[180:181], v[104:105], v[178:179]
	v_sub_u32_e32 v104, v184, v127
	v_cvt_f32_i32_e32 v179, v104
	v_mov_b32_e32 v104, v91
	v_sub_f32_e32 v90, v180, v181
	s_and_b64 vcc, s[74:75], s[0:1]
	v_pk_mul_f32 v[180:181], v[104:105], v[178:179]
	v_sub_u32_e32 v104, v184, v128
	v_cvt_f32_i32_e32 v179, v104
	v_mov_b32_e32 v104, v84
	v_sub_f32_e32 v91, v180, v181
	v_cndmask_b32_e32 v98, v205, v98, vcc
	v_pk_mul_f32 v[180:181], v[104:105], v[178:179]
	v_add_u32_e32 v104, v184, v129
	v_cvt_f32_i32_e32 v179, v104
	v_cmp_gt_i32_e32 vcc, v119, v177
	v_cmp_ge_i32_e64 s[0:1], v184, v119
	s_and_b64 s[0:1], vcc, s[0:1]
	s_and_b64 vcc, s[96:97], s[0:1]
	v_mov_b32_e32 v104, v85
	v_cndmask_b32_e32 v99, v205, v99, vcc
	v_cmp_gt_i32_e32 vcc, v120, v177
	v_cmp_ge_i32_e64 s[0:1], v184, v120
	v_sub_f32_e32 v84, v180, v181
	v_pk_mul_f32 v[180:181], v[104:105], v[178:179]
	v_sub_u32_e32 v104, v184, v130
	s_and_b64 s[0:1], vcc, s[0:1]
	v_cvt_f32_i32_e32 v179, v104
	s_and_b64 vcc, s[4:5], s[0:1]
	v_cndmask_b32_e32 v92, v205, v92, vcc
	v_cmp_ge_i32_e32 vcc, v120, v177
	v_cmp_gt_i32_e64 s[0:1], v184, v120
	s_and_b64 s[0:1], vcc, s[0:1]
	v_mov_b32_e32 v104, v86
	s_and_b64 vcc, s[26:27], s[0:1]
	v_sub_f32_e32 v85, v180, v181
	v_pk_mul_f32 v[180:181], v[104:105], v[178:179]
	v_sub_u32_e32 v104, v184, v131
	v_cndmask_b32_e32 v93, v205, v93, vcc
	v_cmp_gt_i32_e32 vcc, v122, v177
	v_cmp_ge_i32_e64 s[0:1], v184, v122
	v_cvt_f32_i32_e32 v179, v104
	s_and_b64 s[0:1], vcc, s[0:1]
	s_and_b64 vcc, s[20:21], s[0:1]
	v_cndmask_b32_e32 v94, v205, v94, vcc
	v_cmp_gt_i32_e32 vcc, v123, v177
	v_cmp_ge_i32_e64 s[0:1], v184, v123
	v_mov_b32_e32 v104, v87
	s_and_b64 s[0:1], vcc, s[0:1]
	v_sub_f32_e32 v86, v180, v181
	v_pk_mul_f32 v[180:181], v[104:105], v[178:179]
	v_sub_u32_e32 v104, v184, v132
	s_and_b64 vcc, s[44:45], s[0:1]
	v_cvt_f32_i32_e32 v179, v104
	v_cndmask_b32_e32 v95, v205, v95, vcc
	v_cmp_gt_i32_e32 vcc, v124, v177
	v_cmp_ge_i32_e64 s[0:1], v184, v124
	s_and_b64 s[0:1], vcc, s[0:1]
	s_and_b64 vcc, s[46:47], s[0:1]
	v_mov_b32_e32 v104, v80
	v_cndmask_b32_e32 v88, v205, v88, vcc
	v_cmp_ge_i32_e32 vcc, v124, v177
	v_cmp_gt_i32_e64 s[0:1], v184, v124
	v_sub_f32_e32 v87, v180, v181
	v_pk_mul_f32 v[180:181], v[104:105], v[178:179]
	v_add_u32_e32 v104, v184, v133
	s_and_b64 s[0:1], vcc, s[0:1]
	v_cvt_f32_i32_e32 v179, v104
	s_and_b64 vcc, s[48:49], s[0:1]
	v_cndmask_b32_e32 v89, v205, v89, vcc
	v_cmp_gt_i32_e32 vcc, v126, v177
	v_cmp_ge_i32_e64 s[0:1], v184, v126
	s_and_b64 s[0:1], vcc, s[0:1]
	v_mov_b32_e32 v104, v81
	s_and_b64 vcc, s[50:51], s[0:1]
	v_sub_f32_e32 v80, v180, v181
	v_pk_mul_f32 v[180:181], v[104:105], v[178:179]
	v_sub_u32_e32 v104, v184, v134
	v_cndmask_b32_e32 v90, v205, v90, vcc
	v_cmp_gt_i32_e32 vcc, v127, v177
	v_cmp_ge_i32_e64 s[0:1], v184, v127
	v_cvt_f32_i32_e32 v179, v104
	s_and_b64 s[0:1], vcc, s[0:1]
	s_and_b64 vcc, s[52:53], s[0:1]
	v_cndmask_b32_e32 v91, v205, v91, vcc
	v_cmp_gt_i32_e32 vcc, v128, v177
	v_cmp_ge_i32_e64 s[0:1], v184, v128
	v_mov_b32_e32 v104, v82
	s_and_b64 s[0:1], vcc, s[0:1]
	v_sub_f32_e32 v81, v180, v181
	v_pk_mul_f32 v[180:181], v[104:105], v[178:179]
	v_sub_u32_e32 v104, v184, v135
	s_and_b64 vcc, s[54:55], s[0:1]
	v_cvt_f32_i32_e32 v179, v104
	v_cndmask_b32_e32 v84, v205, v84, vcc
	v_cmp_ge_i32_e32 vcc, v128, v177
	v_cmp_gt_i32_e64 s[0:1], v184, v128
	s_and_b64 s[0:1], vcc, s[0:1]
	s_and_b64 vcc, s[56:57], s[0:1]
	v_mov_b32_e32 v104, v83
	v_cndmask_b32_e32 v85, v205, v85, vcc
	v_cmp_gt_i32_e32 vcc, v130, v177
	v_cmp_ge_i32_e64 s[0:1], v184, v130
	v_sub_f32_e32 v82, v180, v181
	v_pk_mul_f32 v[180:181], v[104:105], v[178:179]
	v_sub_u32_e32 v104, v184, v136
	s_and_b64 s[0:1], vcc, s[0:1]
	v_cvt_f32_i32_e32 v179, v104
	s_and_b64 vcc, s[58:59], s[0:1]
	v_cndmask_b32_e32 v86, v205, v86, vcc
	v_cmp_gt_i32_e32 vcc, v131, v177
	v_cmp_ge_i32_e64 s[0:1], v184, v131
	s_and_b64 s[0:1], vcc, s[0:1]
	v_mov_b32_e32 v104, v76
	s_and_b64 vcc, s[42:43], s[0:1]
	v_sub_f32_e32 v83, v180, v181
	v_pk_mul_f32 v[180:181], v[104:105], v[178:179]
; DEV void attn_prompt_group(const Params& p, int l, int item, unsigned char* smem) {
;     ...
; #pragma unroll
;     for (int t = 0; t < 9; ++t)
; #pragma unroll
;       for (int j = 0; j < 4; ++j) {
;         const int si = (w + t) * 16 + fq * 4 + j;
;         const bool ok = (si > qi) && (si <= 128 + qi) && (nb > 0 || si >= 128);
;         const float sc = ok ? s[t][j] * 0.125f - slope * (float)(128 + qi - si) : -INFINITY;
;         s[t][j] = sc; mx = fmaxf(mx, sc);
;       }
;     mx = fmaxf(mx, __shfl_xor(mx, 16)); mx = fmaxf(mx, __shfl_xor(mx, 32));
	v_add_u32_e32 v104, v184, v137
	v_cndmask_b32_e32 v87, v205, v87, vcc
	v_cmp_gt_i32_e32 vcc, v132, v177
	v_cmp_ge_i32_e64 s[0:1], v184, v132
	v_cvt_f32_i32_e32 v179, v104
	s_and_b64 s[0:1], vcc, s[0:1]
	s_and_b64 vcc, s[2:3], s[0:1]
	v_cndmask_b32_e32 v80, v205, v80, vcc
	v_cmp_ge_i32_e32 vcc, v132, v177
	v_cmp_gt_i32_e64 s[0:1], v184, v132
	v_mov_b32_e32 v104, v77
	s_and_b64 s[0:1], vcc, s[0:1]
	v_sub_f32_e32 v76, v180, v181
	v_pk_mul_f32 v[180:181], v[104:105], v[178:179]
	v_sub_u32_e32 v104, v184, v138
	s_and_b64 vcc, s[8:9], s[0:1]
	v_cvt_f32_i32_e32 v179, v104
	v_cndmask_b32_e32 v81, v205, v81, vcc
	v_cmp_gt_i32_e32 vcc, v134, v177
	v_cmp_ge_i32_e64 s[0:1], v184, v134
	s_and_b64 s[0:1], vcc, s[0:1]
	s_and_b64 vcc, s[12:13], s[0:1]
	v_mov_b32_e32 v104, v78
	v_cndmask_b32_e32 v82, v205, v82, vcc
	v_cmp_gt_i32_e32 vcc, v135, v177
	v_cmp_ge_i32_e64 s[0:1], v184, v135
	v_sub_f32_e32 v77, v180, v181
	v_pk_mul_f32 v[180:181], v[104:105], v[178:179]
	v_sub_u32_e32 v104, v184, v139
	s_and_b64 s[0:1], vcc, s[0:1]
	v_cvt_f32_i32_e32 v179, v104
	s_and_b64 vcc, s[14:15], s[0:1]
	v_cndmask_b32_e32 v83, v205, v83, vcc
	v_cmp_gt_i32_e32 vcc, v136, v177
	v_cmp_ge_i32_e64 s[0:1], v184, v136
	s_and_b64 s[0:1], vcc, s[0:1]
	v_mov_b32_e32 v104, v79
	s_and_b64 vcc, s[16:17], s[0:1]
	v_sub_f32_e32 v78, v180, v181
	v_pk_mul_f32 v[180:181], v[104:105], v[178:179]
	v_sub_u32_e32 v104, v184, v140
	v_cndmask_b32_e32 v76, v205, v76, vcc
	v_cmp_ge_i32_e32 vcc, v136, v177
	v_cmp_gt_i32_e64 s[0:1], v184, v136
	v_cvt_f32_i32_e32 v179, v104
	s_and_b64 s[0:1], vcc, s[0:1]
	s_and_b64 vcc, s[76:77], s[0:1]
	v_cndmask_b32_e32 v77, v205, v77, vcc
	v_cmp_gt_i32_e32 vcc, v138, v177
	v_cmp_ge_i32_e64 s[0:1], v184, v138
	v_mov_b32_e32 v104, v72
	s_and_b64 s[0:1], vcc, s[0:1]
	v_sub_f32_e32 v79, v180, v181
	v_pk_mul_f32 v[180:181], v[104:105], v[178:179]
	v_add_u32_e32 v104, v184, v141
	s_and_b64 vcc, s[78:79], s[0:1]
	v_cvt_f32_i32_e32 v179, v104
	v_cndmask_b32_e32 v78, v205, v78, vcc
	v_cmp_gt_i32_e32 vcc, v139, v177
	v_cmp_ge_i32_e64 s[0:1], v184, v139
	s_and_b64 s[0:1], vcc, s[0:1]
	s_and_b64 vcc, s[80:81], s[0:1]
	v_mov_b32_e32 v104, v73
	v_max3_f32 v182, v185, v167, v168
	v_cndmask_b32_e32 v79, v205, v79, vcc
	v_cmp_gt_i32_e32 vcc, v140, v177
	v_cmp_ge_i32_e64 s[0:1], v184, v140
	v_sub_f32_e32 v72, v180, v181
	v_pk_mul_f32 v[180:181], v[104:105], v[178:179]
	v_sub_u32_e32 v104, v184, v142
	v_max3_f32 v182, v182, v96, v97
	s_and_b64 s[0:1], vcc, s[0:1]
	v_cvt_f32_i32_e32 v179, v104
	v_max3_f32 v182, v182, v98, v99
	s_and_b64 vcc, s[82:83], s[0:1]
	v_max3_f32 v182, v182, v92, v93
	v_cndmask_b32_e32 v72, v205, v72, vcc
	v_cmp_ge_i32_e32 vcc, v140, v177
	v_cmp_gt_i32_e64 s[0:1], v184, v140
	v_max3_f32 v182, v182, v94, v95
	s_and_b64 s[0:1], vcc, s[0:1]
	v_mov_b32_e32 v104, v74
	v_max3_f32 v182, v182, v88, v89
	s_and_b64 vcc, s[84:85], s[0:1]
	v_sub_f32_e32 v73, v180, v181
	v_pk_mul_f32 v[180:181], v[104:105], v[178:179]
	v_sub_u32_e32 v104, v184, v143
	v_max3_f32 v182, v182, v90, v91
	v_cndmask_b32_e32 v73, v205, v73, vcc
	v_cmp_gt_i32_e32 vcc, v142, v177
	v_cmp_ge_i32_e64 s[0:1], v184, v142
	v_cvt_f32_i32_e32 v179, v104
	v_max3_f32 v182, v182, v84, v85
	s_and_b64 s[0:1], vcc, s[0:1]
	v_max3_f32 v182, v182, v86, v87
	s_and_b64 vcc, s[86:87], s[0:1]
	v_sub_f32_e32 v74, v180, v181
	v_max3_f32 v182, v182, v80, v81
	v_cndmask_b32_e32 v74, v205, v74, vcc
	v_cmp_gt_i32_e32 vcc, v143, v177
	v_cmp_ge_i32_e64 s[0:1], v184, v143
	v_mov_b32_e32 v104, v75
	v_max3_f32 v182, v182, v82, v83
	s_and_b64 s[0:1], vcc, s[0:1]
	v_pk_mul_f32 v[104:105], v[104:105], v[178:179]
	v_and_b32_e32 v177, 64, v202
	v_max3_f32 v182, v182, v76, v77
	s_and_b64 vcc, s[88:89], s[0:1]
	v_sub_f32_e32 v75, v104, v105
	v_xor_b32_e32 v105, 16, v202
	v_add_u32_e32 v179, 64, v177
	v_max3_f32 v182, v182, v78, v79
	v_cndmask_b32_e32 v75, v205, v75, vcc
	v_cmp_lt_i32_e32 vcc, v105, v179
	v_max3_f32 v182, v182, v72, v73
	v_max3_f32 v104, v182, v74, v75
	v_cndmask_b32_e32 v105, v202, v105, vcc
	v_lshlrev_b32_e32 v105, 2, v105
	ds_bpermute_b32 v180, v105, v104
	s_waitcnt lgkmcnt(0)
	v_max_f32_e32 v180, v180, v180
	v_max_f32_e32 v104, v104, v180
	v_xor_b32_e32 v180, 32, v202
	v_cmp_lt_i32_e32 vcc, v180, v179
	s_nop 1
	v_cndmask_b32_e32 v179, v202, v180, vcc
	v_lshlrev_b32_e32 v179, 2, v179
	ds_bpermute_b32 v180, v179, v104
	s_waitcnt lgkmcnt(0)
; DEV f32x4 mfma16(bf16x4 a, bf16x4 b, f32x4 c) { return __builtin_amdgcn_mfma_f32_16x16x16bf16_1k(a, b, c, 0, 0, 0); }
; DEV void attn_prompt_group(const Params& p, int l, int item, unsigned char* smem) {
;     ...
;     mx = fmaxf(mx, __shfl_xor(mx, 16)); mx = fmaxf(mx, __shfl_xor(mx, 32));
;     float sum = 0.f;
; #pragma unroll
;     for (int t = 0; t < 9; ++t)
; #pragma unroll
;       for (int j = 0; j < 4; ++j) { const float e = __expf(s[t][j] - mx); s[t][j] = e; sum += e; }
;     sum += __shfl_xor(sum, 16); sum += __shfl_xor(sum, 32);
;     const float denom = sum + __expf(sink - mx);
;     f32x4 o[4];
; #pragma unroll
;     for (int dt = 0; dt < 4; ++dt) o[dt] = (f32x4){0.f, 0.f, 0.f, 0.f};
; #pragma unroll
;     for (int t = 0; t < 9; ++t) {
;       const bf16x4 pf = pack4(s[t][0], s[t][1], s[t][2], s[t][3]);
; #pragma unroll
;       for (int dt = 0; dt < 4; ++dt) {
;         const bf16x4 vf = *(const bf16x4*)(Vt + (dt * 16 + fr) * 264 + (w + t) * 16 + fq * 4);
;         o[dt] = mfma16(pf, vf, o[dt]);
;       }
;     }
	v_max_f32_e32 v180, v180, v180
	v_max_f32_e32 v104, v104, v180
	v_sub_f32_e32 v161, v161, v104
	v_mul_f32_e32 v161, 0x3fb8aa3b, v161
	v_sub_f32_e32 v162, v162, v104
	v_exp_f32_e32 v161, v161
	v_mul_f32_e32 v162, 0x3fb8aa3b, v162
	v_sub_f32_e32 v163, v163, v104
	v_exp_f32_e32 v162, v162
	v_mul_f32_e32 v163, 0x3fb8aa3b, v163
	v_sub_f32_e32 v164, v164, v104
	v_exp_f32_e32 v163, v163
	v_mul_f32_e32 v164, 0x3fb8aa3b, v164
	v_sub_f32_e32 v165, v165, v104
	v_exp_f32_e32 v164, v164
	v_mul_f32_e32 v165, 0x3fb8aa3b, v165
	v_sub_f32_e32 v166, v166, v104
	v_add_f32_e32 v180, 0, v161
	v_exp_f32_e32 v165, v165
	v_mul_f32_e32 v166, 0x3fb8aa3b, v166
	v_sub_f32_e32 v167, v167, v104
	v_add_f32_e32 v180, v162, v180
	v_exp_f32_e32 v166, v166
	v_mul_f32_e32 v167, 0x3fb8aa3b, v167
	v_sub_f32_e32 v168, v168, v104
	v_add_f32_e32 v180, v163, v180
	v_exp_f32_e32 v167, v167
	v_mul_f32_e32 v168, 0x3fb8aa3b, v168
	v_sub_f32_e32 v96, v96, v104
	v_add_f32_e32 v180, v164, v180
	v_exp_f32_e32 v168, v168
	v_mul_f32_e32 v96, 0x3fb8aa3b, v96
	v_sub_f32_e32 v97, v97, v104
	v_add_f32_e32 v180, v165, v180
	v_exp_f32_e32 v96, v96
	v_mul_f32_e32 v97, 0x3fb8aa3b, v97
	v_sub_f32_e32 v98, v98, v104
	v_add_f32_e32 v180, v166, v180
	v_exp_f32_e32 v97, v97
	v_mul_f32_e32 v98, 0x3fb8aa3b, v98
	v_sub_f32_e32 v99, v99, v104
	v_add_f32_e32 v180, v167, v180
	v_exp_f32_e32 v98, v98
	v_mul_f32_e32 v99, 0x3fb8aa3b, v99
	v_sub_f32_e32 v92, v92, v104
	v_add_f32_e32 v180, v168, v180
	v_exp_f32_e32 v99, v99
	v_mul_f32_e32 v92, 0x3fb8aa3b, v92
	v_sub_f32_e32 v93, v93, v104
	v_add_f32_e32 v180, v96, v180
	v_exp_f32_e32 v92, v92
	v_mul_f32_e32 v93, 0x3fb8aa3b, v93
	v_sub_f32_e32 v94, v94, v104
	v_add_f32_e32 v180, v97, v180
	v_exp_f32_e32 v93, v93
	v_mul_f32_e32 v94, 0x3fb8aa3b, v94
	v_sub_f32_e32 v95, v95, v104
	v_add_f32_e32 v180, v98, v180
	v_exp_f32_e32 v94, v94
	v_mul_f32_e32 v95, 0x3fb8aa3b, v95
	v_sub_f32_e32 v88, v88, v104
	v_add_f32_e32 v180, v99, v180
	v_exp_f32_e32 v95, v95
	v_mul_f32_e32 v88, 0x3fb8aa3b, v88
	v_add_f32_e32 v180, v92, v180
	v_exp_f32_e32 v181, v88
	v_add_f32_e32 v180, v93, v180
	v_add_f32_e32 v180, v94, v180
	v_sub_f32_e32 v89, v89, v104
	v_add_f32_e32 v180, v95, v180
	v_mul_f32_e32 v89, 0x3fb8aa3b, v89
	v_add_f32_e32 v88, v181, v180
	v_exp_f32_e32 v180, v89
	v_sub_f32_e32 v89, v90, v104
	v_mul_f32_e32 v89, 0x3fb8aa3b, v89
	v_exp_f32_e32 v182, v89
	v_sub_f32_e32 v89, v91, v104
	v_sub_f32_e32 v85, v85, v104
	v_mul_f32_e32 v89, 0x3fb8aa3b, v89
	v_sub_f32_e32 v84, v84, v104
	v_mul_f32_e32 v85, 0x3fb8aa3b, v85
	v_exp_f32_e32 v183, v89
	v_mul_f32_e32 v84, 0x3fb8aa3b, v84
	v_exp_f32_e32 v185, v85
	v_sub_f32_e32 v85, v86, v104
	v_exp_f32_e32 v184, v84
	v_mul_f32_e32 v85, 0x3fb8aa3b, v85
	v_add_f32_e32 v88, v180, v88
	v_exp_f32_e32 v186, v85
	v_sub_f32_e32 v85, v87, v104
	v_sub_f32_e32 v81, v81, v104
	v_add_f32_e32 v88, v182, v88
	v_mul_f32_e32 v85, 0x3fb8aa3b, v85
	v_sub_f32_e32 v80, v80, v104
	v_mul_f32_e32 v81, 0x3fb8aa3b, v81
	v_add_f32_e32 v88, v183, v88
	v_exp_f32_e32 v187, v85
	v_mul_f32_e32 v80, 0x3fb8aa3b, v80
	v_exp_f32_e32 v189, v81
	v_sub_f32_e32 v81, v82, v104
	v_add_f32_e32 v84, v184, v88
	v_exp_f32_e32 v188, v80
	v_mul_f32_e32 v81, 0x3fb8aa3b, v81
	v_add_f32_e32 v84, v185, v84
	v_exp_f32_e32 v190, v81
	v_sub_f32_e32 v81, v83, v104
	v_sub_f32_e32 v77, v77, v104
	v_add_f32_e32 v84, v186, v84
	v_mul_f32_e32 v81, 0x3fb8aa3b, v81
	v_sub_f32_e32 v76, v76, v104
	v_mul_f32_e32 v77, 0x3fb8aa3b, v77
	v_add_f32_e32 v84, v187, v84
	v_exp_f32_e32 v191, v81
	v_mul_f32_e32 v76, 0x3fb8aa3b, v76
	v_exp_f32_e32 v193, v77
	v_sub_f32_e32 v77, v78, v104
	v_add_f32_e32 v80, v188, v84
	v_exp_f32_e32 v192, v76
	v_mul_f32_e32 v77, 0x3fb8aa3b, v77
	v_add_f32_e32 v80, v189, v80
	v_exp_f32_e32 v194, v77
	v_sub_f32_e32 v77, v79, v104
	v_sub_f32_e32 v73, v73, v104
	v_add_f32_e32 v80, v190, v80
	v_mul_f32_e32 v77, 0x3fb8aa3b, v77
	v_sub_f32_e32 v72, v72, v104
	v_mul_f32_e32 v73, 0x3fb8aa3b, v73
	v_add_f32_e32 v80, v191, v80
	v_exp_f32_e32 v195, v77
	v_mul_f32_e32 v72, 0x3fb8aa3b, v72
	v_exp_f32_e32 v197, v73
	v_sub_f32_e32 v73, v74, v104
	v_add_f32_e32 v76, v192, v80
	v_exp_f32_e32 v196, v72
	v_mul_f32_e32 v73, 0x3fb8aa3b, v73
	v_add_f32_e32 v76, v193, v76
	v_exp_f32_e32 v198, v73
	v_sub_f32_e32 v73, v75, v104
	v_add_f32_e32 v76, v194, v76
	v_mul_f32_e32 v73, 0x3fb8aa3b, v73
	v_add_f32_e32 v76, v195, v76
	v_exp_f32_e32 v199, v73
	v_add_f32_e32 v72, v196, v76
	v_add_f32_e32 v72, v197, v72
	v_add_f32_e32 v72, v198, v72
	v_add_f32_e32 v72, v199, v72
	ds_bpermute_b32 v73, v105, v72
	v_cvt_pk_bf16_f32 v84, v161, v162
	v_cvt_pk_bf16_f32 v85, v163, v164
	v_sub_f32_e32 v74, v160, v104
	v_mul_f32_e32 v74, 0x3fb8aa3b, v74
	s_waitcnt lgkmcnt(0)
	v_add_f32_e32 v72, v72, v73
	ds_bpermute_b32 v73, v179, v72
	v_cvt_pk_bf16_f32 v88, v165, v166
	v_cvt_pk_bf16_f32 v89, v167, v168
	ds_read_b64 v[90:91], v148
	v_exp_f32_e32 v104, v74
	s_waitcnt lgkmcnt(1)
	v_add_f32_e32 v105, v72, v73
	ds_read_b64 v[72:73], v147
	ds_read_b64 v[76:77], v147 offset:8448
	ds_read_b64 v[80:81], v147 offset:16896
	ds_read_b64 v[86:87], v147 offset:25344
	s_waitcnt lgkmcnt(3)
	v_mfma_f32_16x16x16_bf16 v[72:75], v[84:85], v[72:73], 0
	v_mfma_f32_16x16x16_bf16 v[72:75], v[88:89], v[90:91], v[72:75]
	ds_read_b64 v[90:91], v148 offset:8448
	s_waitcnt lgkmcnt(3)
	v_mfma_f32_16x16x16_bf16 v[76:79], v[84:85], v[76:77], 0
	s_waitcnt lgkmcnt(0)
	v_mfma_f32_16x16x16_bf16 v[76:79], v[88:89], v[90:91], v[76:79]
	ds_read_b64 v[90:91], v148 offset:16896
	v_mfma_f32_16x16x16_bf16 v[80:83], v[84:85], v[80:81], 0
	s_waitcnt lgkmcnt(0)
	v_mfma_f32_16x16x16_bf16 v[80:83], v[88:89], v[90:91], v[80:83]
	ds_read_b64 v[90:91], v148 offset:25344
	v_mfma_f32_16x16x16_bf16 v[84:87], v[84:85], v[86:87], 0
	s_waitcnt lgkmcnt(0)
; DEV f32x4 mfma16(bf16x4 a, bf16x4 b, f32x4 c) { return __builtin_amdgcn_mfma_f32_16x16x16bf16_1k(a, b, c, 0, 0, 0); }
; DEV void attn_prompt_group(const Params& p, int l, int item, unsigned char* smem) {
;     ...
;     for (int t = 0; t < 9; ++t) {
;       const bf16x4 pf = pack4(s[t][0], s[t][1], s[t][2], s[t][3]);
; #pragma unroll
;       for (int dt = 0; dt < 4; ++dt) {
;         const bf16x4 vf = *(const bf16x4*)(Vt + (dt * 16 + fr) * 264 + (w + t) * 16 + fq * 4);
;         o[dt] = mfma16(pf, vf, o[dt]);
;       }
;     }
;     bf16_t* Os = (bf16_t*)(smem + 33792 + w * 2304);
; #pragma unroll
;     for (int j = 0; j < 4; ++j) {
;       const int r = fq * 4 + j;
;       const float inv = 1.0f / __shfl(denom, r);
	v_mfma_f32_16x16x16_bf16 v[84:87], v[88:89], v[90:91], v[84:87]
	ds_read_b64 v[218:219], v149
	ds_read_b64 v[220:221], v149 offset:8448
	ds_read_b64 v[222:223], v149 offset:16896
	ds_read_b64 v[224:225], v149 offset:25344
	v_cvt_pk_bf16_f32 v88, v96, v97
	v_cvt_pk_bf16_f32 v89, v98, v99
	ds_read_b64 v[226:227], v150
	ds_read_b64 v[228:229], v150 offset:8448
	ds_read_b64 v[230:231], v150 offset:16896
	ds_read_b64 v[232:233], v150 offset:25344
	s_waitcnt lgkmcnt(4)
	v_mfma_f32_16x16x16_bf16 v[72:75], v[88:89], v[218:219], v[72:75]
	v_mfma_f32_16x16x16_bf16 v[76:79], v[88:89], v[220:221], v[76:79]
	v_mfma_f32_16x16x16_bf16 v[80:83], v[88:89], v[222:223], v[80:83]
	v_mfma_f32_16x16x16_bf16 v[84:87], v[88:89], v[224:225], v[84:87]
	v_cvt_pk_bf16_f32 v88, v92, v93
	v_cvt_pk_bf16_f32 v89, v94, v95
	ds_read_b64 v[218:219], v151
	ds_read_b64 v[220:221], v151 offset:8448
	ds_read_b64 v[222:223], v151 offset:16896
	ds_read_b64 v[224:225], v151 offset:25344
	s_waitcnt lgkmcnt(4)
	v_mfma_f32_16x16x16_bf16 v[72:75], v[88:89], v[226:227], v[72:75]
	v_mfma_f32_16x16x16_bf16 v[76:79], v[88:89], v[228:229], v[76:79]
	v_mfma_f32_16x16x16_bf16 v[80:83], v[88:89], v[230:231], v[80:83]
	v_mfma_f32_16x16x16_bf16 v[84:87], v[88:89], v[232:233], v[84:87]
	v_cvt_pk_bf16_f32 v88, v181, v180
	v_cvt_pk_bf16_f32 v89, v182, v183
	ds_read_b64 v[226:227], v152
	ds_read_b64 v[228:229], v152 offset:8448
	ds_read_b64 v[230:231], v152 offset:16896
	ds_read_b64 v[232:233], v152 offset:25344
	s_waitcnt lgkmcnt(4)
	v_mfma_f32_16x16x16_bf16 v[72:75], v[88:89], v[218:219], v[72:75]
	v_mfma_f32_16x16x16_bf16 v[76:79], v[88:89], v[220:221], v[76:79]
	v_mfma_f32_16x16x16_bf16 v[80:83], v[88:89], v[222:223], v[80:83]
	v_mfma_f32_16x16x16_bf16 v[84:87], v[88:89], v[224:225], v[84:87]
	v_cvt_pk_bf16_f32 v88, v184, v185
	v_cvt_pk_bf16_f32 v89, v186, v187
	ds_read_b64 v[218:219], v153
	ds_read_b64 v[220:221], v153 offset:8448
	ds_read_b64 v[222:223], v153 offset:16896
	ds_read_b64 v[224:225], v153 offset:25344
	s_waitcnt lgkmcnt(4)
	v_mfma_f32_16x16x16_bf16 v[72:75], v[88:89], v[226:227], v[72:75]
	v_mfma_f32_16x16x16_bf16 v[76:79], v[88:89], v[228:229], v[76:79]
	v_mfma_f32_16x16x16_bf16 v[80:83], v[88:89], v[230:231], v[80:83]
	v_mfma_f32_16x16x16_bf16 v[84:87], v[88:89], v[232:233], v[84:87]
	v_cvt_pk_bf16_f32 v88, v188, v189
	v_cvt_pk_bf16_f32 v89, v190, v191
	ds_read_b64 v[226:227], v154
	ds_read_b64 v[228:229], v154 offset:8448
	ds_read_b64 v[230:231], v154 offset:16896
	ds_read_b64 v[232:233], v154 offset:25344
	s_waitcnt lgkmcnt(4)
	v_mfma_f32_16x16x16_bf16 v[72:75], v[88:89], v[218:219], v[72:75]
	v_mfma_f32_16x16x16_bf16 v[76:79], v[88:89], v[220:221], v[76:79]
	v_mfma_f32_16x16x16_bf16 v[80:83], v[88:89], v[222:223], v[80:83]
	v_mfma_f32_16x16x16_bf16 v[84:87], v[88:89], v[224:225], v[84:87]
	v_cvt_pk_bf16_f32 v88, v192, v193
	v_cvt_pk_bf16_f32 v89, v194, v195
	ds_read_b64 v[218:219], v155
	ds_read_b64 v[220:221], v155 offset:8448
	ds_read_b64 v[222:223], v155 offset:16896
	ds_read_b64 v[224:225], v155 offset:25344
	s_waitcnt lgkmcnt(4)
	v_mfma_f32_16x16x16_bf16 v[72:75], v[88:89], v[226:227], v[72:75]
	v_mfma_f32_16x16x16_bf16 v[76:79], v[88:89], v[228:229], v[76:79]
	v_mfma_f32_16x16x16_bf16 v[80:83], v[88:89], v[230:231], v[80:83]
	v_mfma_f32_16x16x16_bf16 v[84:87], v[88:89], v[232:233], v[84:87]
	v_cvt_pk_bf16_f32 v88, v196, v197
	v_cvt_pk_bf16_f32 v89, v198, v199
	s_nop 0
	s_waitcnt lgkmcnt(0)
	v_mfma_f32_16x16x16_bf16 v[72:75], v[88:89], v[218:219], v[72:75]
	v_mfma_f32_16x16x16_bf16 v[76:79], v[88:89], v[220:221], v[76:79]
	v_mfma_f32_16x16x16_bf16 v[80:83], v[88:89], v[222:223], v[80:83]
	v_mfma_f32_16x16x16_bf16 v[84:87], v[88:89], v[224:225], v[84:87]
	v_or_b32_e32 v89, v177, v107
	v_add_f32_e32 v88, v104, v105
	v_lshlrev_b32_e32 v89, 2, v89
	ds_bpermute_b32 v89, v89, v88
	s_waitcnt lgkmcnt(0)
; DEV bf16_t f2bf(float f) { return (bf16_t)(cvt_pk_bf16(f, 0.f) & 0xffffu); }
; DEV void attn_prompt_group(const Params& p, int l, int item, unsigned char* smem) {
;     ...
;     bf16_t* Os = (bf16_t*)(smem + 33792 + w * 2304);
; #pragma unroll
;     for (int j = 0; j < 4; ++j) {
;       const int r = fq * 4 + j;
;       const float inv = 1.0f / __shfl(denom, r);
; #pragma unroll
;       for (int dt = 0; dt < 4; ++dt) Os[r * 72 + dt * 16 + fr] = f2bf(o[dt][j] * inv);
;     }
;     asm volatile("s_waitcnt lgkmcnt(0)" ::: "memory");
; #pragma unroll
;     for (int i = 0; i < 2; ++i) {
;       const int c = lane + i * 64, r = c >> 3, kc = c & 7;
;       const u32x4 v = *(const u32x4*)(Os + r * 72 + kc * 8);
;       *(u32x4*)(Z + (rowbase + w * 16 + r) * NIN + AQ + h * 64 + kc * 8) = v;
;     }
;     asm volatile("s_waitcnt lgkmcnt(0)" ::: "memory");
;   }
;   __syncthreads();
	v_div_scale_f32 v90, s[0:1], v89, v89, 1.0
	v_rcp_f32_e32 v91, v90
	s_nop 0
	v_fma_f32 v92, -v90, v91, 1.0
	v_fmac_f32_e32 v91, v92, v91
	v_div_scale_f32 v92, vcc, 1.0, v89, 1.0
	v_mul_f32_e32 v93, v92, v91
	v_fma_f32 v94, -v90, v93, v92
	v_fmac_f32_e32 v93, v94, v91
	v_fma_f32 v90, -v90, v93, v92
	v_div_fmas_f32 v90, v90, v91, v93
	v_div_fixup_f32 v89, v90, v89, 1.0
	v_mul_f32_e32 v72, v72, v89
	v_cvt_pk_bf16_f32 v72, v72, s0
	ds_write_b16 v156, v72 offset:33792
	v_mul_f32_e32 v72, v76, v89
	v_cvt_pk_bf16_f32 v72, v72, s0
	ds_write_b16 v156, v72 offset:33824
	v_mul_f32_e32 v72, v80, v89
	v_cvt_pk_bf16_f32 v72, v72, s0
	ds_write_b16 v156, v72 offset:33856
	v_mul_f32_e32 v72, v84, v89
	v_cvt_pk_bf16_f32 v72, v72, s0
	ds_write_b16 v156, v72 offset:33888
	v_or_b32_e32 v72, v177, v144
	v_lshlrev_b32_e32 v72, 2, v72
	ds_bpermute_b32 v72, v72, v88
	s_waitcnt lgkmcnt(0)
	v_div_scale_f32 v76, s[0:1], v72, v72, 1.0
	v_rcp_f32_e32 v80, v76
	s_nop 0
	v_fma_f32 v84, -v76, v80, 1.0
	v_fmac_f32_e32 v80, v84, v80
	v_div_scale_f32 v84, vcc, 1.0, v72, 1.0
	v_mul_f32_e32 v89, v84, v80
	v_fma_f32 v90, -v76, v89, v84
	v_fmac_f32_e32 v89, v90, v80
	v_fma_f32 v76, -v76, v89, v84
	v_div_fmas_f32 v76, v76, v80, v89
	v_div_fixup_f32 v72, v76, v72, 1.0
	v_mul_f32_e32 v73, v73, v72
	v_cvt_pk_bf16_f32 v73, v73, s0
	ds_write_b16 v157, v73 offset:33792
	v_mul_f32_e32 v73, v77, v72
	v_cvt_pk_bf16_f32 v73, v73, s0
	ds_write_b16 v157, v73 offset:33824
	v_mul_f32_e32 v73, v81, v72
	v_mul_f32_e32 v72, v85, v72
	v_cvt_pk_bf16_f32 v72, v72, s0
	ds_write_b16 v157, v72 offset:33888
	v_or_b32_e32 v72, v177, v145
	v_lshlrev_b32_e32 v72, 2, v72
	ds_bpermute_b32 v72, v72, v88
	v_cvt_pk_bf16_f32 v73, v73, s0
	ds_write_b16 v157, v73 offset:33856
	s_waitcnt lgkmcnt(1)
	v_div_scale_f32 v73, s[0:1], v72, v72, 1.0
	v_rcp_f32_e32 v76, v73
	s_nop 0
	v_fma_f32 v77, -v73, v76, 1.0
	v_fmac_f32_e32 v76, v77, v76
	v_div_scale_f32 v77, vcc, 1.0, v72, 1.0
	v_mul_f32_e32 v80, v77, v76
	v_fma_f32 v81, -v73, v80, v77
	v_fmac_f32_e32 v80, v81, v76
	v_fma_f32 v73, -v73, v80, v77
	v_div_fmas_f32 v73, v73, v76, v80
	v_div_fixup_f32 v72, v73, v72, 1.0
	v_mul_f32_e32 v73, v74, v72
	v_cvt_pk_bf16_f32 v73, v73, s0
	ds_write_b16 v157, v73 offset:33936
	v_mul_f32_e32 v73, v78, v72
	v_cvt_pk_bf16_f32 v73, v73, s0
	ds_write_b16 v157, v73 offset:33968
	v_mul_f32_e32 v73, v82, v72
	v_mul_f32_e32 v72, v86, v72
	v_cvt_pk_bf16_f32 v72, v72, s0
	ds_write_b16 v157, v72 offset:34032
	v_or_b32_e32 v72, v177, v146
	v_lshlrev_b32_e32 v72, 2, v72
	ds_bpermute_b32 v72, v72, v88
	v_cvt_pk_bf16_f32 v73, v73, s0
	ds_write_b16 v157, v73 offset:34000
	s_waitcnt lgkmcnt(1)
	v_div_scale_f32 v73, s[0:1], v72, v72, 1.0
	v_rcp_f32_e32 v74, v73
	s_nop 0
	v_fma_f32 v76, -v73, v74, 1.0
	v_fmac_f32_e32 v74, v76, v74
	v_div_scale_f32 v76, vcc, 1.0, v72, 1.0
	v_mul_f32_e32 v77, v76, v74
	v_fma_f32 v78, -v73, v77, v76
	v_fmac_f32_e32 v77, v78, v74
	v_fma_f32 v73, -v73, v77, v76
	v_div_fmas_f32 v73, v73, v74, v77
	v_div_fixup_f32 v72, v73, v72, 1.0
	v_mul_f32_e32 v73, v75, v72
	v_cvt_pk_bf16_f32 v73, v73, s0
	ds_write_b16 v157, v73 offset:34080
	v_mul_f32_e32 v73, v79, v72
	v_cvt_pk_bf16_f32 v73, v73, s0
	ds_write_b16 v157, v73 offset:34112
	v_mul_f32_e32 v73, v83, v72
	v_mul_f32_e32 v72, v87, v72
	v_cvt_pk_bf16_f32 v73, v73, s0
	v_cvt_pk_bf16_f32 v72, v72, s0
	ds_write_b16 v157, v73 offset:34144
	ds_write_b16 v157, v72 offset:34176
	s_waitcnt lgkmcnt(0)
	ds_read_b128 v[72:75], v158 offset:33792
	v_lshl_add_u64 v[76:77], v[100:101], 0, s[90:91]
	s_mov_b32 s0, 0x4700000
	v_add_co_u32_e32 v78, vcc, s0, v76
	s_mov_b32 s0, 0x471b000
	s_nop 0
	v_addc_co_u32_e32 v79, vcc, 0, v77, vcc
	s_waitcnt lgkmcnt(0)
	global_store_dwordx4 v[78:79], v[72:75], off offset:3072
	ds_read_b128 v[72:75], v159 offset:33792
	v_add_co_u32_e32 v76, vcc, s0, v76
	s_add_u32 s90, s90, 0x80
	s_nop 0
	v_addc_co_u32_e32 v77, vcc, 0, v77, vcc
	s_waitcnt lgkmcnt(0)
	global_store_dwordx4 v[76:77], v[72:75], off offset:3072
	s_addc_u32 s91, s91, 0
	s_waitcnt lgkmcnt(0)
	s_add_u32 s18, s18, 4
	s_addc_u32 s19, s19, 0
	s_add_i32 s6, s6, 1
	s_waitcnt vmcnt(2)
	s_cmpk_lg_i32 s90, 0x200
	s_cbranch_scc1 .LBB0_477
	v_readlane_b32 s76, v248, 47
	v_readlane_b32 s77, v248, 48
	v_readlane_b32 s78, v248, 49
	v_readlane_b32 s79, v248, 50
	v_readlane_b32 s80, v248, 51
	v_readlane_b32 s81, v248, 52
	v_readlane_b32 s82, v248, 53
	v_readlane_b32 s83, v248, 54
	v_readlane_b32 s84, v248, 55
	v_readlane_b32 s85, v248, 56
	v_readlane_b32 s86, v248, 57
	v_readlane_b32 s87, v248, 58
	v_readlane_b32 s88, v248, 59
	v_readlane_b32 s89, v248, 60
	v_readlane_b32 s90, v248, 61
	v_readlane_b32 s91, v248, 62
	s_movk_i32 s75, 0x900
	s_barrier
	s_branch .LBB0_428
